# ffn_up K-loop DMA split six pieces behind the first fragment-read group and two behind the second (other loops four and four)
# baseline (speedup 1.0000x reference)
; #define MFMA16(a, b, c) __builtin_amdgcn_mfma_f32_16x16x32_bf16((a), (b), (c), 0, 0, 0)
; #define RAW_BARRIER() do { asm volatile("s_waitcnt lgkmcnt(0)" ::: "memory"); __builtin_amdgcn_s_barrier(); } while (0)
; template <int AMODE, bool SWAPO = true>
; DI void mainloop_dma16(f32x4 (&acc)[4][2][2][2], const TD& c, const TD& n, bool hasn, bool primed, int& s, int tid) {
;     ...
;     for (int kt = 0; kt < nk; ++kt) {
;         asm volatile("s_waitcnt vmcnt(0)" ::: "memory");
;         RAW_BARRIER();
;         const int ns = s ^ 1, nkt = kt + 1;
;         const bool doload = nkt < nk;
;         const char* sb = smem + s * C::STAGE;
; #pragma unroll
;         for (int k2 = 0; k2 < 2; ++k2) {
;             const int co = ((4 * k2 + q) ^ key) << 4;
;             bf16x8 fw[2][2];
; #pragma unroll
;             for (int ni = 0; ni < 2; ++ni)
; #pragma unroll
;                 for (int rh = 0; rh < 2; ++rh) fw[ni][rh] = *(const bf16x8*)(sb + b_off + (ni * 32 + rh * 16) * 128 + co);
; #pragma unroll
;             for (int mh = 0; mh < 2; ++mh) {
;                 bf16x8 fx[2][2];
; #pragma unroll
;                 for (int m2 = 0; m2 < 2; ++m2)
; #pragma unroll
;                     for (int ch = 0; ch < 2; ++ch) fx[m2][ch] = *(const bf16x8*)(sb + a_off + ((2 * mh + m2) * 32 + ch * 16) * 128 + co);
;                 asm volatile("" ::: "memory");
;                 if (doload) { const int p0 = (2 * k2 + mh) * 2; piece(c, ao, bo, nkt, ns, p0); piece(c, ao, bo, nkt, ns, p0 + 1); }
;                 asm volatile("" ::: "memory");
; #pragma unroll
;                 for (int m2 = 0; m2 < 2; ++m2)
; #pragma unroll
;                     for (int ni = 0; ni < 2; ++ni)
; #pragma unroll
;                         for (int rh = 0; rh < 2; ++rh)
; #pragma unroll
;                             for (int ch = 0; ch < 2; ++ch)
;                                 acc[2 * mh + m2][ni][rh][ch] = SWAPO ? MFMA16(fw[ni][rh], fx[m2][ch], acc[2 * mh + m2][ni][rh][ch]) : MFMA16(fx[m2][ch], fw[ni][rh], acc[2 * mh + m2][ni][rh][ch]);
;             }
.LBB0_1196:
	s_cmp_lt_u32 s27, 15
	s_cselect_b64 s[18:19], -1, 0
	s_lshl_b32 s0, s28, 16
	s_add_i32 s1, s0, 16
	v_add3_u32 v192, s1, v181, v179
	v_add3_u32 v191, s1, v180, v179
	s_waitcnt vmcnt(0)
	v_add_u32_e32 v128, v192, v189
	v_add_u32_e32 v193, v191, v189
	s_waitcnt lgkmcnt(0)
	s_barrier
	ds_read_b128 v[140:143], v128 offset:32768
	ds_read_b128 v[136:139], v128 offset:34816
	ds_read_b128 v[132:135], v128 offset:36864
	ds_read_b128 v[128:131], v128 offset:38912
	ds_read_b128 v[152:155], v193
	ds_read_b128 v[156:159], v193 offset:2048
	ds_read_b128 v[144:147], v193 offset:4096
	ds_read_b128 v[148:151], v193 offset:6144
	s_xor_b32 s0, s0, 0x10000
	s_cmp_gt_u32 s27, 14
	v_add_u32_e32 v176, s0, v188
	s_cbranch_scc1 .LBB0_1198
	v_lshl_add_u64 v[194:195], v[160:161], 0, s[4:5]
	v_readfirstlane_b32 s0, v176
	s_mov_b32 m0, s0
	s_nop 0
	global_load_lds_dwordx4 v[194:195], off
	v_add_u32_e32 v196, 0x400, v176
	v_lshl_add_u64 v[194:195], v[162:163], 0, s[4:5]
	v_readfirstlane_b32 s0, v196
	s_mov_b32 m0, s0
	s_nop 0
	global_load_lds_dwordx4 v[194:195], off
	v_add_u32_e32 v196, 0x800, v176
	v_lshl_add_u64 v[194:195], v[164:165], 0, s[4:5]
	v_readfirstlane_b32 s0, v196
	s_mov_b32 m0, s0
	s_nop 0
	global_load_lds_dwordx4 v[194:195], off
	v_add_u32_e32 v196, 0xc00, v176
	v_lshl_add_u64 v[194:195], v[166:167], 0, s[4:5]
	v_readfirstlane_b32 s0, v196
	s_mov_b32 m0, s0
	s_nop 0
	global_load_lds_dwordx4 v[194:195], off
	v_add_u32_e32 v196, 0x8000, v176
	v_lshl_add_u64 v[194:195], v[168:169], 0, s[4:5]
	v_readfirstlane_b32 s0, v196
	s_mov_b32 m0, s0
	s_nop 0
	global_load_lds_dwordx4 v[194:195], off
	v_add_u32_e32 v196, 0x8400, v176
	v_lshl_add_u64 v[194:195], v[170:171], 0, s[4:5]
	v_readfirstlane_b32 s0, v196
	s_mov_b32 m0, s0
	s_nop 0
	global_load_lds_dwordx4 v[194:195], off
.LBB0_1198:
	s_waitcnt lgkmcnt(0)
	v_mfma_f32_16x16x32_bf16 v[120:123], v[152:155], v[140:143], v[120:123]
	s_andn2_b64 vcc, exec, s[18:19]
	v_mfma_f32_16x16x32_bf16 v[112:115], v[156:159], v[140:143], v[112:115]
	v_mfma_f32_16x16x32_bf16 v[56:59], v[152:155], v[136:139], v[56:59]
	v_mfma_f32_16x16x32_bf16 v[48:51], v[156:159], v[136:139], v[48:51]
	v_mfma_f32_16x16x32_bf16 v[124:127], v[152:155], v[132:135], v[124:127]
	v_mfma_f32_16x16x32_bf16 v[116:119], v[156:159], v[132:135], v[116:119]
	v_mfma_f32_16x16x32_bf16 v[60:63], v[152:155], v[128:131], v[60:63]
	v_mfma_f32_16x16x32_bf16 v[52:55], v[156:159], v[128:131], v[52:55]
	v_mfma_f32_16x16x32_bf16 v[104:107], v[144:147], v[140:143], v[104:107]
	v_mfma_f32_16x16x32_bf16 v[96:99], v[148:151], v[140:143], v[96:99]
	v_mfma_f32_16x16x32_bf16 v[40:43], v[144:147], v[136:139], v[40:43]
	v_mfma_f32_16x16x32_bf16 v[32:35], v[148:151], v[136:139], v[32:35]
	v_mfma_f32_16x16x32_bf16 v[108:111], v[144:147], v[132:135], v[108:111]
	v_mfma_f32_16x16x32_bf16 v[100:103], v[148:151], v[132:135], v[100:103]
	v_mfma_f32_16x16x32_bf16 v[44:47], v[144:147], v[128:131], v[44:47]
	v_mfma_f32_16x16x32_bf16 v[36:39], v[148:151], v[128:131], v[36:39]
	ds_read_b128 v[152:155], v193 offset:8192
	ds_read_b128 v[156:159], v193 offset:10240
	ds_read_b128 v[144:147], v193 offset:12288
	ds_read_b128 v[148:151], v193 offset:14336
	v_cndmask_b32_e64 v193, 0, 1, s[18:19]
	v_cmp_ne_u32_e64 s[0:1], 1, v193
	s_cbranch_vccnz .LBB0_1200
	v_add_u32_e32 v196, 0x8800, v176
	v_lshl_add_u64 v[194:195], v[172:173], 0, s[4:5]
	v_readfirstlane_b32 s18, v196
	s_mov_b32 m0, s18
	s_nop 0
	global_load_lds_dwordx4 v[194:195], off
	v_add_u32_e32 v196, 0x8c00, v176
	v_lshl_add_u64 v[194:195], v[174:175], 0, s[4:5]
	v_readfirstlane_b32 s18, v196
	s_mov_b32 m0, s18
	s_nop 0
	global_load_lds_dwordx4 v[194:195], off
